# attention A: half-tile stagger of waves 4-7 (K tile written to LDS before a new mid-tile barrier, 2 buffers kept)
# baseline (speedup 1.0000x reference)
; DI unsigned pk2(float lo, float hi) { f32v2 v = {lo, hi}; bf16v2 b = __builtin_convertvector(v, bf16v2); return __builtin_bit_cast(unsigned, b); }
; DI float lo16(unsigned w) { return __uint_as_float(w << 16); }
; DI float hi16(unsigned w) { return __uint_as_float(w & 0xffff0000u); }
; DI float silu(float g) { return g * __builtin_amdgcn_rcpf(1.f + __expf(-g)); }
; template <int DQK, bool MB> ...
;     ...
;     if (ST && grp == 0) { asm volatile("" ::: "memory"); __builtin_amdgcn_s_barrier(); asm volatile("" ::: "memory"); }
; template <bool DOA, bool DOB>
; DI void p4_attention(const Args& a, LAS unsigned char* lds, int G) {
;     ...
;             for (int ct = 0; ct < 2; ++ct) { const float inv = __builtin_amdgcn_rcpf(lsum[ct]); const size_t m = (size_t)b * L + (ct ? qi1 : qi0);
;                 const bf16_t* gp = PROJ + m * LDP + C_GA + hd * 128 + 4 * q; bf16_t* op = OCAT + m * 4096 + hd * 128 + 4 * q;
; #pragma unroll
;                 for (int dt = 0; dt < 8; ++dt) { const u32x2 g = *(const u32x2*)(gp + 16 * dt); const f32x4 v = o[ct][dt] * inv;
;                     u32x2 w; w.x = pk2(v[0] * silu(lo16(g.x)), v[1] * silu(hi16(g.x))); w.y = pk2(v[2] * silu(lo16(g.y)), v[3] * silu(hi16(g.y)));
;                     *(u32x2*)(op + 16 * dt) = w; } }
.LBB0_494:
	v_ashrrev_i32_e32 v0, 2, v196
	v_and_b32_e32 v0, -4, v0
	v_ashrrev_i32_e32 v1, 31, v0
	v_lshl_add_u64 v[8:9], s[20:21], 0, v[176:177]
	v_mov_b64_e32 v[10:11], s[54:55]
	v_lshlrev_b64 v[2:3], 1, v[0:1]
	v_mad_u64_u32 v[0:1], s[0:1], v8, s42, v[10:11]
	s_lshl_b32 s4, s4, 8
	v_mad_i32_i24 v1, v9, s42, v1
	v_lshl_add_u64 v[0:1], v[0:1], 0, s[4:5]
	v_lshl_add_u64 v[0:1], v[0:1], 0, v[2:3]
	v_add_co_u32_e32 v4, vcc, s43, v0
	s_nop 1
	v_addc_co_u32_e32 v5, vcc, 0, v1, vcc
	s_barrier
	v_readfirstlane_b32 s98, v224
	s_nop 3
	s_cmp_gt_u32 s98, 0xff
	s_cbranch_scc1 .Lst_a_g1_skip
	s_barrier
.Lst_a_g1_skip:
	global_load_dwordx2 v[4:5], v[4:5], off offset:3904
	v_lshl_add_u64 v[0:1], v[0:1], 0, s[18:19]
	global_load_dwordx2 v[6:7], v[0:1], off offset:32
	global_load_dwordx2 v[28:29], v[0:1], off offset:64
	global_load_dwordx2 v[26:27], v[0:1], off offset:96
	global_load_dwordx2 v[24:25], v[0:1], off offset:128
	v_cmp_lt_i32_e32 vcc, v186, v188
	s_add_u32 s0, s30, s4
	s_addc_u32 s1, s31, 0
	v_cndmask_b32_e32 v14, v187, v186, vcc
	v_lshlrev_b32_e32 v14, 2, v14
	ds_bpermute_b32 v20, v14, v183
	v_cmp_lt_i32_e32 vcc, v189, v188
	v_lshlrev_b64 v[8:9], 13, v[8:9]
	v_lshl_add_u64 v[16:17], s[0:1], 0, v[2:3]
	v_cndmask_b32_e32 v15, v187, v189, vcc
	v_lshlrev_b32_e32 v15, 2, v15
	ds_bpermute_b32 v14, v14, v182
	v_lshl_add_u64 v[18:19], v[16:17], 0, v[8:9]
	s_waitcnt lgkmcnt(1)
	v_add_f32_e32 v8, v183, v20
	ds_bpermute_b32 v9, v15, v8
	v_lshl_add_u64 v[12:13], s[20:21], 0, v[178:179]
	s_waitcnt lgkmcnt(1)
	v_add_f32_e32 v21, v182, v14
	ds_bpermute_b32 v30, v15, v21
	v_mad_u64_u32 v[10:11], s[22:23], v12, s42, v[10:11]
	s_waitcnt lgkmcnt(1)
	v_add_f32_e32 v8, v8, v9
	v_rcp_f32_e32 v20, v8
	s_waitcnt lgkmcnt(0)
	v_add_f32_e32 v48, v21, v30
	v_mad_i32_i24 v11, v13, s42, v11
	v_lshl_add_u64 v[10:11], v[10:11], 0, s[4:5]
	v_pk_mul_f32 v[30:31], v[174:175], v[20:21] op_sel_hi:[1,0]
	v_pk_mul_f32 v[32:33], v[172:173], v[20:21] op_sel_hi:[1,0]
	v_pk_mul_f32 v[34:35], v[170:171], v[20:21] op_sel_hi:[1,0]
	v_pk_mul_f32 v[36:37], v[168:169], v[20:21] op_sel_hi:[1,0]
	v_lshl_add_u64 v[22:23], v[10:11], 0, v[2:3]
	v_lshl_add_u64 v[2:3], v[22:23], 0, s[18:19]
	global_load_dwordx2 v[14:15], v[2:3], off offset:64
	global_load_dwordx2 v[10:11], v[2:3], off offset:96
	global_load_dwordx2 v[8:9], v[2:3], off offset:128
	v_add_co_u32_e32 v22, vcc, s43, v22
	s_add_i32 s60, s60, 1
	s_nop 0
	v_addc_co_u32_e32 v23, vcc, 0, v23, vcc
	s_cmp_eq_u32 s60, 4
	global_load_dwordx2 v[22:23], v[22:23], off offset:3904
	s_waitcnt vmcnt(8)
	v_lshlrev_b32_e32 v38, 16, v4
	v_and_b32_e32 v39, 0xffff0000, v4
	v_lshlrev_b32_e32 v4, 16, v5
	v_and_b32_e32 v5, 0xffff0000, v5
	s_waitcnt vmcnt(7)
	v_lshlrev_b32_e32 v40, 16, v6
	v_mul_f32_e32 v43, 0xbfb8aa3b, v4
	v_mul_f32_e32 v44, 0xbfb8aa3b, v5
	v_mul_f32_e32 v45, 0xbfb8aa3b, v40
	v_exp_f32_e32 v43, v43
	v_exp_f32_e32 v44, v44
	v_exp_f32_e32 v45, v45
	v_mul_f32_e32 v21, 0xbfb8aa3b, v38
	v_mul_f32_e32 v42, 0xbfb8aa3b, v39
	v_exp_f32_e32 v21, v21
	v_exp_f32_e32 v42, v42
	v_add_f32_e32 v51, 1.0, v43
	v_add_f32_e32 v52, 1.0, v44
	v_and_b32_e32 v41, 0xffff0000, v6
	v_lshlrev_b32_e32 v6, 16, v7
	v_and_b32_e32 v7, 0xffff0000, v7
	v_add_f32_e32 v53, 1.0, v45
	v_rcp_f32_e32 v44, v51
	v_rcp_f32_e32 v45, v52
	v_mul_f32_e32 v46, 0xbfb8aa3b, v41
	v_mul_f32_e32 v47, 0xbfb8aa3b, v6
	v_mul_f32_e32 v49, 0xbfb8aa3b, v7
	v_exp_f32_e32 v46, v46
	v_exp_f32_e32 v50, v47
	v_exp_f32_e32 v49, v49
	v_add_f32_e32 v21, 1.0, v21
	v_add_f32_e32 v47, 1.0, v42
	v_rcp_f32_e32 v42, v21
	v_rcp_f32_e32 v43, v47
	v_pk_mul_f32 v[4:5], v[44:45], v[4:5]
	v_add_f32_e32 v21, 1.0, v46
	v_pk_mul_f32 v[4:5], v[30:31], v[4:5]
	v_rcp_f32_e32 v46, v53
	v_cvt_pk_bf16_f32 v31, v4, v5
	v_add_f32_e32 v4, 1.0, v50
	v_add_f32_e32 v5, 1.0, v49
	v_rcp_f32_e32 v47, v21
	v_rcp_f32_e32 v4, v4
	v_rcp_f32_e32 v5, v5
	v_pk_mul_f32 v[38:39], v[42:43], v[38:39]
	v_pk_mul_f32 v[4:5], v[4:5], v[6:7]
	v_pk_mul_f32 v[32:33], v[32:33], v[38:39]
	v_pk_mul_f32 v[4:5], v[34:35], v[4:5]
	v_cvt_pk_bf16_f32 v30, v32, v33
	global_store_dwordx2 v[18:19], v[30:31], off
	v_pk_mul_f32 v[30:31], v[46:47], v[40:41]
	s_waitcnt vmcnt(7)
	v_lshlrev_b32_e32 v6, 16, v28
	v_pk_mul_f32 v[30:31], v[36:37], v[30:31]
	v_and_b32_e32 v7, 0xffff0000, v28
	v_cvt_pk_bf16_f32 v30, v30, v31
	v_cvt_pk_bf16_f32 v31, v4, v5
	v_pk_mul_f32 v[4:5], v[166:167], v[20:21] op_sel_hi:[1,0]
	v_mul_f32_e32 v21, 0xbfb8aa3b, v6
	v_exp_f32_e32 v21, v21
	v_mul_f32_e32 v28, 0xbfb8aa3b, v7
	v_exp_f32_e32 v32, v28
	global_store_dwordx2 v[18:19], v[30:31], off offset:32
	v_pk_mul_f32 v[30:31], v[164:165], v[20:21] op_sel_hi:[1,0]
	v_add_f32_e32 v21, 1.0, v21
	v_rcp_f32_e32 v28, v21
	v_add_f32_e32 v21, 1.0, v32
	v_lshlrev_b32_e32 v32, 16, v29
	v_and_b32_e32 v33, 0xffff0000, v29
	v_mul_f32_e32 v29, 0xbfb8aa3b, v32
	v_exp_f32_e32 v36, v29
	v_mul_f32_e32 v29, 0xbfb8aa3b, v33
	v_exp_f32_e32 v37, v29
	v_rcp_f32_e32 v29, v21
	v_add_f32_e32 v21, 1.0, v36
	v_rcp_f32_e32 v36, v21
	v_add_f32_e32 v21, 1.0, v37
	v_rcp_f32_e32 v37, v21
	v_pk_mul_f32 v[6:7], v[28:29], v[6:7]
	global_load_dwordx2 v[34:35], v[0:1], off offset:160
	v_pk_mul_f32 v[6:7], v[30:31], v[6:7]
	v_pk_mul_f32 v[28:29], v[36:37], v[32:33]
	v_cvt_pk_bf16_f32 v6, v6, v7
	v_pk_mul_f32 v[4:5], v[4:5], v[28:29]
	s_waitcnt vmcnt(8)
; DI unsigned pk2(float lo, float hi) { f32v2 v = {lo, hi}; bf16v2 b = __builtin_convertvector(v, bf16v2); return __builtin_bit_cast(unsigned, b); }
; DI float lo16(unsigned w) { return __uint_as_float(w << 16); }
; DI float hi16(unsigned w) { return __uint_as_float(w & 0xffff0000u); }
; DI float silu(float g) { return g * __builtin_amdgcn_rcpf(1.f + __expf(-g)); }
; template <bool DOA, bool DOB>
; DI void p4_attention(const Args& a, LAS unsigned char* lds, int G) {
;     ...
;             for (int ct = 0; ct < 2; ++ct) { const float inv = __builtin_amdgcn_rcpf(lsum[ct]); const size_t m = (size_t)b * L + (ct ? qi1 : qi0);
;                 const bf16_t* gp = PROJ + m * LDP + C_GA + hd * 128 + 4 * q; bf16_t* op = OCAT + m * 4096 + hd * 128 + 4 * q;
; #pragma unroll
;                 for (int dt = 0; dt < 8; ++dt) { const u32x2 g = *(const u32x2*)(gp + 16 * dt); const f32x4 v = o[ct][dt] * inv;
;                     u32x2 w; w.x = pk2(v[0] * silu(lo16(g.x)), v[1] * silu(hi16(g.x))); w.y = pk2(v[2] * silu(lo16(g.y)), v[3] * silu(hi16(g.y)));
;                     *(u32x2*)(op + 16 * dt) = w; } }
	v_and_b32_e32 v31, 0xffff0000, v27
	v_cvt_pk_bf16_f32 v7, v4, v5
	global_store_dwordx2 v[18:19], v[6:7], off offset:64
	v_lshlrev_b32_e32 v6, 16, v26
	v_pk_mul_f32 v[4:5], v[162:163], v[20:21] op_sel_hi:[1,0]
	v_and_b32_e32 v7, 0xffff0000, v26
	v_mul_f32_e32 v21, 0xbfb8aa3b, v6
	v_exp_f32_e32 v21, v21
	v_mul_f32_e32 v26, 0xbfb8aa3b, v7
	v_exp_f32_e32 v30, v26
	global_load_dwordx2 v[32:33], v[0:1], off offset:192
	v_pk_mul_f32 v[28:29], v[160:161], v[20:21] op_sel_hi:[1,0]
	v_add_f32_e32 v21, 1.0, v21
	v_rcp_f32_e32 v26, v21
	v_add_f32_e32 v21, 1.0, v30
	v_lshlrev_b32_e32 v30, 16, v27
	v_mul_f32_e32 v27, 0xbfb8aa3b, v30
	v_exp_f32_e32 v36, v27
	v_mul_f32_e32 v27, 0xbfb8aa3b, v31
	v_exp_f32_e32 v37, v27
	v_rcp_f32_e32 v27, v21
	v_add_f32_e32 v21, 1.0, v36
	v_rcp_f32_e32 v36, v21
	v_add_f32_e32 v21, 1.0, v37
	v_rcp_f32_e32 v37, v21
	v_pk_mul_f32 v[6:7], v[26:27], v[6:7]
	v_pk_mul_f32 v[26:27], v[36:37], v[30:31]
	v_pk_mul_f32 v[6:7], v[28:29], v[6:7]
	v_pk_mul_f32 v[4:5], v[4:5], v[26:27]
	v_cvt_pk_bf16_f32 v6, v6, v7
	v_cvt_pk_bf16_f32 v7, v4, v5
	global_store_dwordx2 v[18:19], v[6:7], off offset:96
	s_waitcnt vmcnt(10)
	v_lshlrev_b32_e32 v6, 16, v24
	v_pk_mul_f32 v[4:5], v[158:159], v[20:21] op_sel_hi:[1,0]
	v_and_b32_e32 v7, 0xffff0000, v24
	v_mul_f32_e32 v21, 0xbfb8aa3b, v6
	v_exp_f32_e32 v21, v21
	v_mul_f32_e32 v24, 0xbfb8aa3b, v7
	v_exp_f32_e32 v28, v24
	v_and_b32_e32 v29, 0xffff0000, v25
	v_pk_mul_f32 v[26:27], v[156:157], v[20:21] op_sel_hi:[1,0]
	v_add_f32_e32 v21, 1.0, v21
	v_rcp_f32_e32 v24, v21
	v_add_f32_e32 v21, 1.0, v28
	v_lshlrev_b32_e32 v28, 16, v25
	v_mul_f32_e32 v25, 0xbfb8aa3b, v28
	v_exp_f32_e32 v30, v25
	v_mul_f32_e32 v25, 0xbfb8aa3b, v29
	v_exp_f32_e32 v31, v25
	v_rcp_f32_e32 v25, v21
	v_add_f32_e32 v21, 1.0, v30
	v_rcp_f32_e32 v30, v21
	v_add_f32_e32 v21, 1.0, v31
	v_rcp_f32_e32 v31, v21
	v_pk_mul_f32 v[6:7], v[24:25], v[6:7]
	v_pk_mul_f32 v[24:25], v[30:31], v[28:29]
	v_pk_mul_f32 v[6:7], v[26:27], v[6:7]
	v_pk_mul_f32 v[4:5], v[4:5], v[24:25]
	v_cvt_pk_bf16_f32 v6, v6, v7
	v_cvt_pk_bf16_f32 v7, v4, v5
	global_store_dwordx2 v[18:19], v[6:7], off offset:128
	global_load_dwordx2 v[6:7], v[2:3], off offset:32
	v_pk_mul_f32 v[4:5], v[154:155], v[20:21] op_sel_hi:[1,0]
	global_load_dwordx2 v[0:1], v[0:1], off offset:224
	s_waitcnt vmcnt(6)
	v_lshlrev_b32_e32 v24, 16, v34
	v_and_b32_e32 v25, 0xffff0000, v34
	v_mul_f32_e32 v21, 0xbfb8aa3b, v24
	v_exp_f32_e32 v21, v21
	v_mul_f32_e32 v26, 0xbfb8aa3b, v25
	v_exp_f32_e32 v29, v26
	v_lshlrev_b32_e32 v30, 16, v35
	v_pk_mul_f32 v[26:27], v[152:153], v[20:21] op_sel_hi:[1,0]
	v_add_f32_e32 v21, 1.0, v21
	v_rcp_f32_e32 v28, v21
	v_add_f32_e32 v21, 1.0, v29
	v_and_b32_e32 v31, 0xffff0000, v35
	v_mul_f32_e32 v29, 0xbfb8aa3b, v30
	v_exp_f32_e32 v34, v29
	v_mul_f32_e32 v29, 0xbfb8aa3b, v31
	v_exp_f32_e32 v35, v29
	v_rcp_f32_e32 v29, v21
	v_add_f32_e32 v21, 1.0, v34
	v_rcp_f32_e32 v34, v21
	v_add_f32_e32 v21, 1.0, v35
	v_rcp_f32_e32 v35, v21
	v_pk_mul_f32 v[24:25], v[28:29], v[24:25]
	s_nop 0
	v_pk_mul_f32 v[24:25], v[26:27], v[24:25]
	v_pk_mul_f32 v[26:27], v[34:35], v[30:31]
	v_cvt_pk_bf16_f32 v24, v24, v25
	v_pk_mul_f32 v[4:5], v[4:5], v[26:27]
	s_waitcnt vmcnt(4)
	v_lshlrev_b32_e32 v30, 16, v33
	v_cvt_pk_bf16_f32 v25, v4, v5
	global_store_dwordx2 v[18:19], v[24:25], off offset:160
	v_lshlrev_b32_e32 v24, 16, v32
	v_pk_mul_f32 v[4:5], v[150:151], v[20:21] op_sel_hi:[1,0]
	v_and_b32_e32 v25, 0xffff0000, v32
	v_mul_f32_e32 v21, 0xbfb8aa3b, v24
	v_exp_f32_e32 v21, v21
	v_mul_f32_e32 v26, 0xbfb8aa3b, v25
	v_exp_f32_e32 v29, v26
	v_and_b32_e32 v31, 0xffff0000, v33
	v_pk_mul_f32 v[26:27], v[148:149], v[20:21] op_sel_hi:[1,0]
	v_add_f32_e32 v21, 1.0, v21
	v_rcp_f32_e32 v28, v21
	v_add_f32_e32 v21, 1.0, v29
	v_mul_f32_e32 v29, 0xbfb8aa3b, v30
	v_exp_f32_e32 v32, v29
	v_mul_f32_e32 v29, 0xbfb8aa3b, v31
	v_exp_f32_e32 v33, v29
	v_rcp_f32_e32 v29, v21
	v_add_f32_e32 v21, 1.0, v32
	v_rcp_f32_e32 v32, v21
	v_add_f32_e32 v21, 1.0, v33
	v_rcp_f32_e32 v33, v21
	v_pk_mul_f32 v[24:25], v[28:29], v[24:25]
	s_nop 0
	v_pk_mul_f32 v[24:25], v[26:27], v[24:25]
	v_pk_mul_f32 v[26:27], v[32:33], v[30:31]
	v_cvt_pk_bf16_f32 v24, v24, v25
	v_pk_mul_f32 v[4:5], v[4:5], v[26:27]
	s_waitcnt vmcnt(1)
	v_and_b32_e32 v27, 0xffff0000, v1
	v_cvt_pk_bf16_f32 v25, v4, v5
	global_store_dwordx2 v[18:19], v[24:25], off offset:192
	v_and_b32_e32 v25, 0xffff0000, v0
	v_pk_mul_f32 v[4:5], v[146:147], v[20:21] op_sel_hi:[1,0]
	v_mul_f32_e32 v21, 0xbfb8aa3b, v25
	v_exp_f32_e32 v26, v21
	v_lshlrev_b32_e32 v24, 16, v0
	v_mul_f32_e32 v0, 0xbfb8aa3b, v24
	v_exp_f32_e32 v0, v0
	v_add_f32_e32 v28, 1.0, v26
	v_lshlrev_b32_e32 v26, 16, v1
	v_mul_f32_e32 v1, 0xbfb8aa3b, v26
	v_exp_f32_e32 v29, v1
	v_mul_f32_e32 v1, 0xbfb8aa3b, v27
	v_exp_f32_e32 v30, v1
	v_add_f32_e32 v0, 1.0, v0
	v_rcp_f32_e32 v0, v0
	v_rcp_f32_e32 v1, v28
	v_add_f32_e32 v28, 1.0, v29
	v_add_f32_e32 v29, 1.0, v30
	v_rcp_f32_e32 v28, v28
	v_rcp_f32_e32 v29, v29
	v_pk_mul_f32 v[20:21], v[144:145], v[20:21] op_sel_hi:[1,0]
	v_pk_mul_f32 v[0:1], v[0:1], v[24:25]
	s_nop 0
	v_pk_mul_f32 v[0:1], v[20:21], v[0:1]
	v_pk_mul_f32 v[20:21], v[28:29], v[26:27]
	v_cvt_pk_bf16_f32 v0, v0, v1
	v_pk_mul_f32 v[4:5], v[4:5], v[20:21]
	s_nop 0
	v_cvt_pk_bf16_f32 v1, v4, v5
	v_rcp_f32_e32 v4, v48
	global_store_dwordx2 v[18:19], v[0:1], off offset:224
	v_lshlrev_b64 v[0:1], 13, v[12:13]
	v_lshl_add_u64 v[0:1], v[16:17], 0, v[0:1]
	v_lshlrev_b32_e32 v16, 16, v22
	v_pk_mul_f32 v[12:13], v[142:143], v[4:5] op_sel_hi:[1,0]
	v_and_b32_e32 v17, 0xffff0000, v22
	v_mul_f32_e32 v5, 0xbfb8aa3b, v16
	v_exp_f32_e32 v5, v5
	v_mul_f32_e32 v18, 0xbfb8aa3b, v17
	v_exp_f32_e32 v21, v18
	v_lshlrev_b32_e32 v22, 16, v23
; DI unsigned pk2(float lo, float hi) { f32v2 v = {lo, hi}; bf16v2 b = __builtin_convertvector(v, bf16v2); return __builtin_bit_cast(unsigned, b); }
; DI float lo16(unsigned w) { return __uint_as_float(w << 16); }
; DI float hi16(unsigned w) { return __uint_as_float(w & 0xffff0000u); }
; DI float silu(float g) { return g * __builtin_amdgcn_rcpf(1.f + __expf(-g)); }
; template <bool DOA, bool DOB>
; DI void p4_attention(const Args& a, LAS unsigned char* lds, int G) {
;     ...
;             for (int ct = 0; ct < 2; ++ct) { const float inv = __builtin_amdgcn_rcpf(lsum[ct]); const size_t m = (size_t)b * L + (ct ? qi1 : qi0);
;                 const bf16_t* gp = PROJ + m * LDP + C_GA + hd * 128 + 4 * q; bf16_t* op = OCAT + m * 4096 + hd * 128 + 4 * q;
; #pragma unroll
;                 for (int dt = 0; dt < 8; ++dt) { const u32x2 g = *(const u32x2*)(gp + 16 * dt); const f32x4 v = o[ct][dt] * inv;
;                     u32x2 w; w.x = pk2(v[0] * silu(lo16(g.x)), v[1] * silu(hi16(g.x))); w.y = pk2(v[2] * silu(lo16(g.y)), v[3] * silu(hi16(g.y)));
;                     *(u32x2*)(op + 16 * dt) = w; } }
	v_pk_mul_f32 v[18:19], v[140:141], v[4:5] op_sel_hi:[1,0]
	v_add_f32_e32 v5, 1.0, v5
	v_rcp_f32_e32 v20, v5
	v_add_f32_e32 v5, 1.0, v21
	v_and_b32_e32 v23, 0xffff0000, v23
	v_mul_f32_e32 v21, 0xbfb8aa3b, v22
	v_exp_f32_e32 v24, v21
	v_mul_f32_e32 v21, 0xbfb8aa3b, v23
	v_exp_f32_e32 v25, v21
	v_rcp_f32_e32 v21, v5
	v_add_f32_e32 v5, 1.0, v24
	v_rcp_f32_e32 v24, v5
	v_add_f32_e32 v5, 1.0, v25
	v_rcp_f32_e32 v25, v5
	v_pk_mul_f32 v[16:17], v[20:21], v[16:17]
	v_and_b32_e32 v21, 0xffff0000, v7
	v_pk_mul_f32 v[16:17], v[18:19], v[16:17]
	v_pk_mul_f32 v[18:19], v[24:25], v[22:23]
	v_cvt_pk_bf16_f32 v16, v16, v17
	v_pk_mul_f32 v[12:13], v[12:13], v[18:19]
	s_nop 0
	v_cvt_pk_bf16_f32 v17, v12, v13
	global_store_dwordx2 v[0:1], v[16:17], off
	v_lshlrev_b32_e32 v16, 16, v6
	v_pk_mul_f32 v[12:13], v[138:139], v[4:5] op_sel_hi:[1,0]
	v_and_b32_e32 v17, 0xffff0000, v6
	v_mul_f32_e32 v5, 0xbfb8aa3b, v16
	v_exp_f32_e32 v5, v5
	v_mul_f32_e32 v6, 0xbfb8aa3b, v17
	v_exp_f32_e32 v20, v6
	v_pk_mul_f32 v[18:19], v[136:137], v[4:5] op_sel_hi:[1,0]
	v_add_f32_e32 v5, 1.0, v5
	v_rcp_f32_e32 v6, v5
	v_add_f32_e32 v5, 1.0, v20
	v_lshlrev_b32_e32 v20, 16, v7
	v_mul_f32_e32 v7, 0xbfb8aa3b, v20
	v_exp_f32_e32 v22, v7
	v_mul_f32_e32 v7, 0xbfb8aa3b, v21
	v_exp_f32_e32 v23, v7
	v_rcp_f32_e32 v7, v5
	v_add_f32_e32 v5, 1.0, v22
	v_rcp_f32_e32 v22, v5
	v_add_f32_e32 v5, 1.0, v23
	v_rcp_f32_e32 v23, v5
	v_pk_mul_f32 v[6:7], v[6:7], v[16:17]
	v_pk_mul_f32 v[16:17], v[22:23], v[20:21]
	v_pk_mul_f32 v[6:7], v[18:19], v[6:7]
	v_pk_mul_f32 v[12:13], v[12:13], v[16:17]
	v_cvt_pk_bf16_f32 v6, v6, v7
	v_cvt_pk_bf16_f32 v7, v12, v13
	v_lshlrev_b32_e32 v12, 16, v14
	global_store_dwordx2 v[0:1], v[6:7], off offset:32
	v_pk_mul_f32 v[6:7], v[134:135], v[4:5] op_sel_hi:[1,0]
	v_and_b32_e32 v13, 0xffff0000, v14
	v_mul_f32_e32 v5, 0xbfb8aa3b, v12
	v_exp_f32_e32 v5, v5
	v_mul_f32_e32 v14, 0xbfb8aa3b, v13
	v_exp_f32_e32 v18, v14
	v_lshlrev_b32_e32 v20, 16, v15
	v_pk_mul_f32 v[16:17], v[132:133], v[4:5] op_sel_hi:[1,0]
	v_add_f32_e32 v5, 1.0, v5
	v_rcp_f32_e32 v14, v5
	v_add_f32_e32 v5, 1.0, v18
	global_load_dwordx2 v[18:19], v[2:3], off offset:160
	v_and_b32_e32 v21, 0xffff0000, v15
	v_mul_f32_e32 v15, 0xbfb8aa3b, v20
	v_exp_f32_e32 v22, v15
	v_mul_f32_e32 v15, 0xbfb8aa3b, v21
	v_exp_f32_e32 v23, v15
	v_rcp_f32_e32 v15, v5
	v_add_f32_e32 v5, 1.0, v22
	v_rcp_f32_e32 v22, v5
	v_add_f32_e32 v5, 1.0, v23
	v_pk_mul_f32 v[12:13], v[14:15], v[12:13]
	v_rcp_f32_e32 v23, v5
	v_pk_mul_f32 v[12:13], v[16:17], v[12:13]
	global_load_dwordx2 v[16:17], v[2:3], off offset:192
	v_cvt_pk_bf16_f32 v12, v12, v13
	v_pk_mul_f32 v[14:15], v[22:23], v[20:21]
	global_load_dwordx2 v[2:3], v[2:3], off offset:224
	v_pk_mul_f32 v[6:7], v[6:7], v[14:15]
	v_lshlrev_b32_e32 v14, 16, v10
	v_cvt_pk_bf16_f32 v13, v6, v7
	global_store_dwordx2 v[0:1], v[12:13], off offset:64
	v_pk_mul_f32 v[6:7], v[130:131], v[4:5] op_sel_hi:[1,0]
	v_pk_mul_f32 v[12:13], v[128:129], v[4:5] op_sel_hi:[1,0]
	v_mul_f32_e32 v5, 0xbfb8aa3b, v14
	v_and_b32_e32 v15, 0xffff0000, v10
	v_exp_f32_e32 v5, v5
	v_mul_f32_e32 v10, 0xbfb8aa3b, v15
	v_exp_f32_e32 v20, v10
	v_and_b32_e32 v21, 0xffff0000, v11
	v_add_f32_e32 v5, 1.0, v5
	v_rcp_f32_e32 v10, v5
	v_add_f32_e32 v5, 1.0, v20
	v_lshlrev_b32_e32 v20, 16, v11
	v_mul_f32_e32 v11, 0xbfb8aa3b, v20
	v_exp_f32_e32 v22, v11
	v_mul_f32_e32 v11, 0xbfb8aa3b, v21
	v_exp_f32_e32 v23, v11
	v_rcp_f32_e32 v11, v5
	v_add_f32_e32 v5, 1.0, v22
	v_rcp_f32_e32 v22, v5
	v_add_f32_e32 v5, 1.0, v23
	v_rcp_f32_e32 v23, v5
	v_pk_mul_f32 v[10:11], v[10:11], v[14:15]
	v_and_b32_e32 v15, 0xffff0000, v9
	v_pk_mul_f32 v[10:11], v[12:13], v[10:11]
	v_pk_mul_f32 v[12:13], v[22:23], v[20:21]
	v_cvt_pk_bf16_f32 v10, v10, v11
	v_pk_mul_f32 v[6:7], v[6:7], v[12:13]
	v_lshlrev_b32_e32 v12, 16, v8
	v_cvt_pk_bf16_f32 v11, v6, v7
	global_store_dwordx2 v[0:1], v[10:11], off offset:96
	v_pk_mul_f32 v[6:7], v[126:127], v[4:5] op_sel_hi:[1,0]
	v_pk_mul_f32 v[10:11], v[124:125], v[4:5] op_sel_hi:[1,0]
	v_mul_f32_e32 v5, 0xbfb8aa3b, v12
	v_and_b32_e32 v13, 0xffff0000, v8
	v_exp_f32_e32 v5, v5
	v_mul_f32_e32 v8, 0xbfb8aa3b, v13
	v_exp_f32_e32 v14, v8
	v_add_f32_e32 v5, 1.0, v5
	v_rcp_f32_e32 v8, v5
	v_add_f32_e32 v5, 1.0, v14
	v_lshlrev_b32_e32 v14, 16, v9
	v_mul_f32_e32 v9, 0xbfb8aa3b, v14
	v_exp_f32_e32 v20, v9
	v_mul_f32_e32 v9, 0xbfb8aa3b, v15
	v_exp_f32_e32 v21, v9
	v_rcp_f32_e32 v9, v5
	v_add_f32_e32 v5, 1.0, v20
	v_rcp_f32_e32 v20, v5
	v_add_f32_e32 v5, 1.0, v21
	v_rcp_f32_e32 v21, v5
	v_pk_mul_f32 v[8:9], v[8:9], v[12:13]
	s_nop 0
	v_pk_mul_f32 v[8:9], v[10:11], v[8:9]
	v_pk_mul_f32 v[10:11], v[20:21], v[14:15]
	v_cvt_pk_bf16_f32 v8, v8, v9
	v_pk_mul_f32 v[6:7], v[6:7], v[10:11]
	s_waitcnt vmcnt(4)
	v_lshlrev_b32_e32 v14, 16, v19
	v_cvt_pk_bf16_f32 v9, v6, v7
	global_store_dwordx2 v[0:1], v[8:9], off offset:128
	v_lshlrev_b32_e32 v8, 16, v18
	v_pk_mul_f32 v[6:7], v[122:123], v[4:5] op_sel_hi:[1,0]
	v_and_b32_e32 v9, 0xffff0000, v18
	v_mul_f32_e32 v5, 0xbfb8aa3b, v8
	v_exp_f32_e32 v5, v5
	v_mul_f32_e32 v10, 0xbfb8aa3b, v9
	v_exp_f32_e32 v13, v10
	v_and_b32_e32 v15, 0xffff0000, v19
	v_pk_mul_f32 v[10:11], v[120:121], v[4:5] op_sel_hi:[1,0]
	v_add_f32_e32 v5, 1.0, v5
	v_rcp_f32_e32 v12, v5
	v_add_f32_e32 v5, 1.0, v13
	v_mul_f32_e32 v13, 0xbfb8aa3b, v14
	v_exp_f32_e32 v18, v13
	v_mul_f32_e32 v13, 0xbfb8aa3b, v15
	v_exp_f32_e32 v19, v13
	v_rcp_f32_e32 v13, v5
	v_add_f32_e32 v5, 1.0, v18
	v_rcp_f32_e32 v18, v5
	v_add_f32_e32 v5, 1.0, v19
	v_rcp_f32_e32 v19, v5
	v_pk_mul_f32 v[8:9], v[12:13], v[8:9]
	s_nop 0
	v_pk_mul_f32 v[8:9], v[10:11], v[8:9]
	v_pk_mul_f32 v[10:11], v[18:19], v[14:15]
	v_cvt_pk_bf16_f32 v8, v8, v9
	v_pk_mul_f32 v[6:7], v[6:7], v[10:11]
	s_waitcnt vmcnt(4)
; DI unsigned pk2(float lo, float hi) { f32v2 v = {lo, hi}; bf16v2 b = __builtin_convertvector(v, bf16v2); return __builtin_bit_cast(unsigned, b); }
; DI float lo16(unsigned w) { return __uint_as_float(w << 16); }
; DI float hi16(unsigned w) { return __uint_as_float(w & 0xffff0000u); }
; DI float silu(float g) { return g * __builtin_amdgcn_rcpf(1.f + __expf(-g)); }
; template <bool DOA, bool DOB>
; DI void p4_attention(const Args& a, LAS unsigned char* lds, int G) {
;     ...
;         for (int j = 0; j < 4; ++j) {
;     ...
;             for (int ct = 0; ct < 2; ++ct) { const float inv = __builtin_amdgcn_rcpf(lsum[ct]); const size_t m = (size_t)b * L + (ct ? qi1 : qi0);
;                 const bf16_t* gp = PROJ + m * LDP + C_GA + hd * 128 + 4 * q; bf16_t* op = OCAT + m * 4096 + hd * 128 + 4 * q;
; #pragma unroll
;                 for (int dt = 0; dt < 8; ++dt) { const u32x2 g = *(const u32x2*)(gp + 16 * dt); const f32x4 v = o[ct][dt] * inv;
;                     u32x2 w; w.x = pk2(v[0] * silu(lo16(g.x)), v[1] * silu(hi16(g.x))); w.y = pk2(v[2] * silu(lo16(g.y)), v[3] * silu(hi16(g.y)));
;                     *(u32x2*)(op + 16 * dt) = w; } }
	v_lshlrev_b32_e32 v14, 16, v17
	v_cvt_pk_bf16_f32 v9, v6, v7
	global_store_dwordx2 v[0:1], v[8:9], off offset:160
	v_lshlrev_b32_e32 v8, 16, v16
	v_pk_mul_f32 v[6:7], v[78:79], v[4:5] op_sel_hi:[1,0]
	v_and_b32_e32 v9, 0xffff0000, v16
	v_mul_f32_e32 v5, 0xbfb8aa3b, v8
	v_exp_f32_e32 v5, v5
	v_mul_f32_e32 v10, 0xbfb8aa3b, v9
	v_exp_f32_e32 v13, v10
	v_and_b32_e32 v15, 0xffff0000, v17
	v_pk_mul_f32 v[10:11], v[76:77], v[4:5] op_sel_hi:[1,0]
	v_add_f32_e32 v5, 1.0, v5
	v_rcp_f32_e32 v12, v5
	v_add_f32_e32 v5, 1.0, v13
	v_mul_f32_e32 v13, 0xbfb8aa3b, v14
	v_exp_f32_e32 v16, v13
	v_mul_f32_e32 v13, 0xbfb8aa3b, v15
	v_exp_f32_e32 v17, v13
	v_rcp_f32_e32 v13, v5
	v_add_f32_e32 v5, 1.0, v16
	v_rcp_f32_e32 v16, v5
	v_add_f32_e32 v5, 1.0, v17
	v_rcp_f32_e32 v17, v5
	v_pk_mul_f32 v[8:9], v[12:13], v[8:9]
	s_nop 0
	v_pk_mul_f32 v[8:9], v[10:11], v[8:9]
	v_pk_mul_f32 v[10:11], v[16:17], v[14:15]
	v_cvt_pk_bf16_f32 v8, v8, v9
	v_pk_mul_f32 v[6:7], v[6:7], v[10:11]
	s_waitcnt vmcnt(4)
	v_and_b32_e32 v11, 0xffff0000, v3
	v_cvt_pk_bf16_f32 v9, v6, v7
	global_store_dwordx2 v[0:1], v[8:9], off offset:192
	v_and_b32_e32 v9, 0xffff0000, v2
	v_pk_mul_f32 v[6:7], v[74:75], v[4:5] op_sel_hi:[1,0]
	v_mul_f32_e32 v5, 0xbfb8aa3b, v9
	v_exp_f32_e32 v10, v5
	v_lshlrev_b32_e32 v8, 16, v2
	v_mul_f32_e32 v2, 0xbfb8aa3b, v8
	v_exp_f32_e32 v2, v2
	v_add_f32_e32 v12, 1.0, v10
	v_lshlrev_b32_e32 v10, 16, v3
	v_mul_f32_e32 v3, 0xbfb8aa3b, v10
	v_exp_f32_e32 v13, v3
	v_mul_f32_e32 v3, 0xbfb8aa3b, v11
	v_exp_f32_e32 v14, v3
	v_add_f32_e32 v2, 1.0, v2
	v_rcp_f32_e32 v2, v2
	v_rcp_f32_e32 v3, v12
	v_add_f32_e32 v12, 1.0, v13
	v_add_f32_e32 v13, 1.0, v14
	v_rcp_f32_e32 v12, v12
	v_rcp_f32_e32 v13, v13
	v_pk_mul_f32 v[4:5], v[72:73], v[4:5] op_sel_hi:[1,0]
	v_pk_mul_f32 v[2:3], v[2:3], v[8:9]
	s_nop 0
	v_pk_mul_f32 v[2:3], v[4:5], v[2:3]
	v_pk_mul_f32 v[4:5], v[12:13], v[10:11]
	v_cvt_pk_bf16_f32 v2, v2, v3
	v_pk_mul_f32 v[4:5], v[6:7], v[4:5]
	s_nop 0
	v_cvt_pk_bf16_f32 v3, v4, v5
	global_store_dwordx2 v[0:1], v[2:3], off offset:224
	s_cbranch_scc1 .LBB0_492
; #define LAS __attribute__((address_space(3)))
; template <int DQK, bool MB> ...
;     ...
;     for (int kk = 0; kk < KH; ++kk) { qf[0][kk] = *(const bf16x8*)(q0p + 32 * kk + 8 * q); qf[1][kk] = *(const bf16x8*)(q1p + 32 * kk + 8 * q); }
; #pragma unroll
;     for (int ct = 0; ct < 2; ++ct) { lsum[ct] = 0.f;
; #pragma unroll
;         for (int dt = 0; dt < 8; ++dt) o[ct][dt] = (f32x4){0.f, 0.f, 0.f, 0.f}; }
;     float mrow[2] = {-1e30f, -1e30f};
;     float tbfar = 0.f; if (MB) tbfar = tb[128 * 16 + r];
;     const int skey = tid >> 3, sch = tid & 7;
;     const int kgo0 = skey * DQK + sch * 8;
;     int klo0; { const int st = (skey >> 4) * KK + (sch >> 2), ob = (skey & 15) * 64 + (sch & 3) * 16; klo0 = st * 1024 + (ob ^ (((ob >> 9) & 1) << 5)); }
;     const int vgo0 = skey * L + sch * 8, vlo0 = skey * VT_PITCH + sch * 16;
;     u32x4 kreg[KCH], vreg[2];
; #pragma unroll
;     for (int i = 0; i < KCH; ++i) kreg[i] = *(const u32x4*)(Kg + kgo0 + 64 * i);
; #pragma unroll
;     for (int i = 0; i < 2; ++i) vreg[i] = *(const u32x4*)(Vtg + vgo0 + 64 * i * L);
; #pragma unroll
;     for (int i = 0; i < KCH; ++i) *(LAS u32x4*)(kbase + klo0 + 2048 * i) = kreg[i];
; #pragma unroll
;     for (int i = 0; i < 2; ++i) { *(LAS u32x2*)(vbase + vlo0 + 64 * VT_PITCH * i) = (u32x2){vreg[i].x, vreg[i].y}; *(LAS u32x2*)(vbase + vlo0 + 64 * VT_PITCH * i + 8) = (u32x2){vreg[i].z, vreg[i].w}; }
;     if (ST && nt > 1) {
; #pragma unroll
;         for (int i = 0; i < KCH; ++i) kreg[i] = *(const u32x4*)(Kg + (size_t)64 * DQK + kgo0 + 64 * i);
; #pragma unroll
;         for (int i = 0; i < 2; ++i) vreg[i] = *(const u32x4*)(Vtg + 64 + vgo0 + 64 * i * L);
; #pragma unroll
;         for (int i = 0; i < KCH; ++i) *(LAS u32x4*)(kbase + KT_BYTES + klo0 + 2048 * i) = kreg[i];
; #pragma unroll
;         for (int i = 0; i < 2; ++i) { *(LAS u32x2*)(vbase + VT_BYTES + vlo0 + 64 * VT_PITCH * i) = (u32x2){vreg[i].x, vreg[i].y}; *(LAS u32x2*)(vbase + VT_BYTES + vlo0 + 64 * VT_PITCH * i + 8) = (u32x2){vreg[i].z, vreg[i].w}; }
;     }
;     __syncthreads();
;     const int grp = __builtin_amdgcn_readfirstlane(tid >> 8);
; #pragma unroll
;     for (int kk = 0; kk < KH; ++kk) asm volatile("" :: "v"(qf[0][kk]), "v"(qf[1][kk]));
;     if (ST && grp == 1) { asm volatile("" ::: "memory"); __builtin_amdgcn_s_barrier(); asm volatile("" ::: "memory"); }
.LBB0_495:
	s_lshr_b32 s4, s60, 1
	s_add_i32 s0, s51, s4
	s_or_b32 s4, s4, s48
	s_ashr_i32 s1, s0, 31
	s_or_b32 s62, s4, s49
	s_lshl_b64 s[22:23], s[0:1], 19
	s_ashr_i32 s63, s62, 31
	s_mul_i32 s61, s62, 0xc0000
	s_mul_hi_i32 s1, s62, 0xc0000
	s_add_u32 s64, s24, s61
	s_addc_u32 s65, s25, s1
	s_lshl_b64 s[62:63], s[62:63], 19
	s_add_u32 s62, s26, s62
	s_addc_u32 s63, s27, s63
	s_add_u32 s66, s52, s61
	s_addc_u32 s67, s53, s1
	s_bitcmp0_b32 s60, 0
	s_cselect_b32 s1, s50, s47
	s_lshl_b32 s1, s1, 8
	v_mov_b32_e32 v196, v191
	s_add_i32 s61, s1, s33
	v_mov_b32_e32 v30, v224
	v_and_or_b32 v176, v196, 15, s61
	v_or_b32_e32 v178, 16, v176
	v_mov_b64_e32 v[0:1], s[66:67]
	v_mad_u64_u32 v[2:3], s[66:67], v176, s36, v[0:1]
	v_bfe_u32 v31, v30, 4, 2
	v_mad_u64_u32 v[0:1], s[66:67], v178, s36, v[0:1]
	v_lshlrev_b32_e32 v20, 4, v31
	v_mov_b32_e32 v21, v177
	v_lshl_add_u64 v[22:23], v[2:3], 0, v[20:21]
	v_lshl_add_u64 v[24:25], v[0:1], 0, v[20:21]
	v_ashrrev_i32_e32 v21, 3, v30
	v_and_b32_e32 v32, 7, v30
	v_mul_lo_u32 v0, v21, s37
	v_lshlrev_b32_e32 v1, 3, v32
	v_or_b32_e32 v0, v0, v1
	v_lshl_or_b32 v8, v21, 11, v1
	v_ashrrev_i32_e32 v1, 31, v0
	v_lshlrev_b64 v[26:27], 1, v[0:1]
	v_ashrrev_i32_e32 v9, 31, v8
	v_lshl_add_u64 v[10:11], s[64:65], 0, v[26:27]
	v_lshlrev_b64 v[28:29], 1, v[8:9]
	global_load_dwordx4 v[64:67], v[22:23], off
	global_load_dwordx4 v[68:71], v[22:23], off offset:64
	global_load_dwordx4 v[0:3], v[10:11], off
	global_load_dwordx4 v[4:7], v[10:11], off offset:128
	v_lshl_add_u64 v[16:17], s[62:63], 0, v[28:29]
	global_load_dwordx4 v[8:11], v[10:11], off offset:256
	s_nop 0
	global_load_dwordx4 v[12:15], v[16:17], off
	v_add_co_u32_e32 v16, vcc, s39, v16
	v_lshlrev_b32_e32 v33, 2, v21
	s_nop 0
	v_addc_co_u32_e32 v17, vcc, 0, v17, vcc
	global_load_dwordx4 v[16:19], v[16:17], off
	s_nop 0
	global_load_dwordx4 v[108:111], v[24:25], off
	global_load_dwordx4 v[88:91], v[24:25], off offset:64
	global_load_dwordx4 v[92:95], v[22:23], off offset:128
	global_load_dwordx4 v[80:83], v[22:23], off offset:192
	global_load_dwordx4 v[112:115], v[24:25], off offset:128
	global_load_dwordx4 v[96:99], v[24:25], off offset:192
	global_load_dwordx4 v[100:103], v[22:23], off offset:256
	global_load_dwordx4 v[84:87], v[22:23], off offset:320
	global_load_dwordx4 v[116:119], v[24:25], off offset:256
	global_load_dwordx4 v[104:107], v[24:25], off offset:320
	v_lshrrev_b32_e32 v22, 7, v30
	v_bfe_u32 v23, v30, 2, 1
	v_lshlrev_b32_e32 v24, 4, v30
	v_lshlrev_b32_e32 v25, 6, v21
	v_mul_lo_u32 v22, v22, 6
	v_and_b32_e32 v24, 48, v24
	v_lshlrev_b32_e32 v32, 4, v32
	v_mul_lo_u32 v21, v21, s38
	v_and_b32_e32 v25, 0x3c0, v25
	v_and_b32_e32 v33, 32, v33
	v_or_b32_e32 v22, v22, v23
	v_add3_u32 v200, 0, v21, v32
	v_bitop3_b32 v21, v25, v33, v24 bitop3:0x36
	v_lshlrev_b32_e32 v22, 10, v22
	v_add3_u32 v201, 0, v21, v22
	v_add_u32_e32 v23, 0xc000, v200
	v_add_u32_e32 v24, 0xe200, v200
	v_lshl_add_u32 v197, v31, 3, 0
	v_lshlrev_b32_e32 v199, 2, v31
	s_or_b32 s62, s1, 0xc0
	v_lshl_add_u64 v[164:165], s[22:23], 0, v[28:29]
	v_mad_i64_i32 v[166:167], s[0:1], s0, v192, v[26:27]
	s_mov_b32 s63, 0
	v_mov_b32_e32 v179, v177
	s_or_b32 s64, s61, 31
	v_mov_b32_e32 v180, v177
	v_mov_b32_e32 v181, v177
	v_mov_b32_e32 v184, 0xf149f2ca
	v_mov_b32_e32 v185, 0xf149f2ca
	s_mov_b32 s22, 0
	s_waitcnt vmcnt(14)
	ds_write_b128 v201, v[0:3]
	s_waitcnt vmcnt(13)
	ds_write_b128 v201, v[4:7] offset:2048
	s_waitcnt vmcnt(12)
	ds_write_b128 v201, v[8:11] offset:4096
	s_waitcnt vmcnt(11)
	ds_write2_b64 v23, v[12:13], v[14:15] offset1:1
	s_waitcnt vmcnt(10)
	ds_write2_b64 v24, v[16:17], v[18:19] offset1:1
	v_and_b32_e32 v0, 15, v30
	v_lshlrev_b32_e32 v2, 2, v30
	v_lshlrev_b32_e32 v1, 6, v0
	v_and_b32_e32 v2, 32, v2
	v_bitop3_b32 v202, v20, v2, v1 bitop3:0x36
	v_mov_b32_e32 v2, v177
	v_mov_b32_e32 v3, v177
	v_mul_u32_u24_e32 v198, 0x88, v0
	v_mad_u32_u24 v204, v0, s38, v197
	v_mov_b32_e32 v0, v177
	v_mov_b32_e32 v1, v177
	v_mov_b64_e32 v[6:7], v[2:3]
	v_mov_b64_e32 v[10:11], v[2:3]
	v_mov_b64_e32 v[14:15], v[2:3]
	v_mov_b64_e32 v[18:19], v[2:3]
	v_mov_b64_e32 v[22:23], v[2:3]
	v_mov_b64_e32 v[26:27], v[2:3]
	v_mov_b64_e32 v[30:31], v[2:3]
	v_mov_b64_e32 v[34:35], v[2:3]
	v_mov_b64_e32 v[38:39], v[2:3]
	v_mov_b64_e32 v[42:43], v[2:3]
	v_mov_b64_e32 v[46:47], v[2:3]
	v_mov_b64_e32 v[50:51], v[2:3]
	v_mov_b64_e32 v[54:55], v[2:3]
	v_mov_b64_e32 v[58:59], v[2:3]
	v_mov_b64_e32 v[62:63], v[2:3]
	v_add_u32_e32 v203, 0, v202
	v_mov_b64_e32 v[4:5], v[0:1]
	v_mov_b64_e32 v[8:9], v[0:1]
	v_mov_b64_e32 v[12:13], v[0:1]
	v_mov_b64_e32 v[16:17], v[0:1]
	v_mov_b64_e32 v[20:21], v[0:1]
	v_mov_b64_e32 v[24:25], v[0:1]
	v_mov_b64_e32 v[28:29], v[0:1]
	v_mov_b64_e32 v[32:33], v[0:1]
	v_mov_b64_e32 v[36:37], v[0:1]
	v_mov_b64_e32 v[40:41], v[0:1]
	v_mov_b64_e32 v[44:45], v[0:1]
	v_mov_b64_e32 v[48:49], v[0:1]
	v_mov_b64_e32 v[52:53], v[0:1]
	v_mov_b64_e32 v[56:57], v[0:1]
	v_mov_b64_e32 v[60:61], v[0:1]
	s_waitcnt lgkmcnt(0)
	s_barrier
	v_readfirstlane_b32 s98, v224
	s_nop 3
	s_cmp_lt_u32 s98, 0x100
	s_cbranch_scc1 .Lst_a_g0_skip
	s_barrier
.Lst_a_g0_skip:
	s_waitcnt vmcnt(9)
	s_waitcnt vmcnt(8)
	s_waitcnt vmcnt(5)
	s_waitcnt vmcnt(4)
	s_waitcnt vmcnt(1)
	s_waitcnt vmcnt(0)
	s_branch .LBB0_498

; template <int DQK, bool MB> ...
;     ...
;         const bool pre = (kt + AHEAD < nt);
;         if (pre) {
; #pragma unroll
;             for (int i = 0; i < KCH; ++i) kreg[i] = *(const u32x4*)(Kg + (size_t)(kt + AHEAD) * 64 * DQK + kgo0 + 64 * i);
; #pragma unroll
;             for (int i = 0; i < 2; ++i) vreg[i] = *(const u32x4*)(Vtg + (kt + AHEAD) * 64 + vgo0 + 64 * i * L);
;         }
;         const bool act = MB || 64 * kt <= wave_qmax;
;         const LAS unsigned char* kb = kbase + buf * KT_BYTES; const LAS unsigned char* vb = vbase + buf * VT_BYTES;
;         f32x4 s[4][2];
;         if (act) {
;             bf16x8 kfa[KK], kfb[KK];
; #pragma unroll
;             for (int kk = 0; kk < KK; ++kk) kfa[kk] = *(const LAS bf16x8*)(kb + kk * 1024 + koff);
; #pragma unroll
;             for (int ks = 0; ks < 4; ++ks) {
;                 if (ks < 3) {
; #pragma unroll
;                     for (int kk = 0; kk < KK; ++kk) { const bf16x8 t = *(const LAS bf16x8*)(kb + ((ks + 1) * KK + kk) * 1024 + koff); if (ks & 1) kfa[kk] = t; else kfb[kk] = t; }
;                 }
;                 __builtin_amdgcn_sched_barrier(0);
;                 s[ks][0] = (f32x4){0.f, 0.f, 0.f, 0.f}; s[ks][1] = (f32x4){0.f, 0.f, 0.f, 0.f};
; #pragma unroll
;                 for (int kk = 0; kk < KK; ++kk) { const bf16x8 kf = (ks & 1) ? kfb[kk] : kfa[kk];
;                     const bf16x8 qa0 = qf[0][kk], qa1 = qf[1][kk];
;                     s[ks][0] = __builtin_amdgcn_mfma_f32_16x16x32_bf16(kf, qa0, s[ks][0], 0, 0, 0);
;                     s[ks][1] = __builtin_amdgcn_mfma_f32_16x16x32_bf16(kf, qa1, s[ks][1], 0, 0, 0); }
;                 __builtin_amdgcn_sched_barrier(0);
;             }
;         }
;         if (ST) { asm volatile("" ::: "memory"); __builtin_amdgcn_s_barrier(); asm volatile("" ::: "memory"); }
;     ...
;         if (pre) { const int nb = ST ? ((buf == 0) ? 2 : buf - 1) : (buf ^ 1); LAS unsigned char* kbn = kbase + nb * KT_BYTES; LAS unsigned char* vbn = vbase + nb * VT_BYTES;
; #pragma unroll
;             for (int i = 0; i < KCH; ++i) *(LAS u32x4*)(kbn + klo0 + 2048 * i) = kreg[i];
; #pragma unroll
;             for (int i = 0; i < 2; ++i) { *(LAS u32x2*)(vbn + vlo0 + 64 * VT_PITCH * i) = (u32x2){vreg[i].x, vreg[i].y}; *(LAS u32x2*)(vbn + vlo0 + 64 * VT_PITCH * i + 8) = (u32x2){vreg[i].z, vreg[i].w}; } }
;         __syncthreads();
.LBB0_497:
	s_xor_b32 s22, s22, 1
	s_mul_i32 s65, s22, 0x6000
	s_mul_i32 s23, s22, 0x4400
	v_add_u32_e32 v72, s23, v200
	s_add_i32 s63, s63, 64
	v_add_u32_e32 v73, 0xc000, v72
	v_add_u32_e32 v72, 0xe200, v72
	v_lshl_add_u64 v[164:165], v[164:165], 0, s[6:7]
	s_cmp_eq_u32 s62, s63
	v_lshl_add_u64 v[166:167], v[166:167], 0, s[10:11]
	s_waitcnt vmcnt(1)
	ds_write2_b64 v73, v[120:121], v[122:123] offset1:1
	s_waitcnt vmcnt(0)
	ds_write2_b64 v72, v[128:129], v[130:131] offset1:1
	s_waitcnt lgkmcnt(0)
	s_barrier
	s_cbranch_scc1 .LBB0_501
.LBB0_498:
	v_lshl_add_u64 v[72:73], s[52:53], 0, v[166:167]
	v_add_co_u32_e32 v120, vcc, s40, v72
	v_lshl_add_u64 v[128:129], s[52:53], 0, v[164:165]
	s_nop 0
	v_addc_co_u32_e32 v121, vcc, 0, v73, vcc
	v_add_co_u32_e32 v122, vcc, 0xc000000, v128
	global_load_dwordx4 v[72:75], v[120:121], off
	global_load_dwordx4 v[76:79], v[120:121], off offset:128
	v_addc_co_u32_e32 v123, vcc, 0, v129, vcc
	v_add_co_u32_e32 v128, vcc, 0xc040000, v128
	global_load_dwordx4 v[124:127], v[120:121], off offset:256
	s_nop 0
	global_load_dwordx4 v[120:123], v[122:123], off offset:128
	v_addc_co_u32_e32 v129, vcc, 0, v129, vcc
	global_load_dwordx4 v[128:131], v[128:129], off offset:128
	s_cmp_gt_u32 s63, s64
	s_cbranch_scc1 .Lst_a_noact
	s_mul_i32 s0, s22, 0x6000
	v_add_u32_e32 v182, s0, v203
	ds_read_b128 v[132:135], v182
	ds_read_b128 v[136:139], v182 offset:1024
	ds_read_b128 v[140:143], v182 offset:2048
	ds_read_b128 v[144:147], v182 offset:3072
	ds_read_b128 v[148:151], v182 offset:4096
	ds_read_b128 v[152:155], v182 offset:5120
	ds_read_b128 v[156:159], v182 offset:6144
	ds_read_b128 v[160:163], v182 offset:7168
	ds_read_b128 v[168:171], v182 offset:8192
	ds_read_b128 v[172:175], v182 offset:9216
	ds_read_b128 v[186:189], v182 offset:10240
	ds_read_b128 v[206:209], v182 offset:11264
	s_waitcnt lgkmcnt(11)
	v_mfma_f32_16x16x32_bf16 v[210:213], v[132:135], v[64:67], 0
	v_mfma_f32_16x16x32_bf16 v[132:135], v[132:135], v[108:111], 0
	s_waitcnt lgkmcnt(10)
	v_mfma_f32_16x16x32_bf16 v[210:213], v[136:139], v[68:71], v[210:213]
	v_mfma_f32_16x16x32_bf16 v[132:135], v[136:139], v[88:91], v[132:135]
	s_waitcnt lgkmcnt(9)
	v_mfma_f32_16x16x32_bf16 v[136:139], v[140:143], v[92:95], v[210:213]
	v_mfma_f32_16x16x32_bf16 v[132:135], v[140:143], v[112:115], v[132:135]
	s_waitcnt lgkmcnt(8)
	v_mfma_f32_16x16x32_bf16 v[136:139], v[144:147], v[80:83], v[136:139]
	v_mfma_f32_16x16x32_bf16 v[132:135], v[144:147], v[96:99], v[132:135]
	s_waitcnt lgkmcnt(7)
	v_mfma_f32_16x16x32_bf16 v[136:139], v[148:151], v[100:103], v[136:139]
	v_mfma_f32_16x16x32_bf16 v[132:135], v[148:151], v[116:119], v[132:135]
	s_waitcnt lgkmcnt(6)
	v_mfma_f32_16x16x32_bf16 v[148:151], v[152:155], v[84:87], v[136:139]
	v_mfma_f32_16x16x32_bf16 v[136:139], v[152:155], v[104:107], v[132:135]
	s_nop 4
	ds_read_b128 v[132:135], v182 offset:12288
	ds_read_b128 v[140:143], v182 offset:13312
	ds_read_b128 v[152:155], v182 offset:14336
	ds_read_b128 v[210:213], v182 offset:15360
	ds_read_b128 v[214:217], v182 offset:16384
	ds_read_b128 v[218:221], v182 offset:17408
	s_waitcnt lgkmcnt(11)
	v_mfma_f32_16x16x32_bf16 v[144:147], v[156:159], v[64:67], 0
	v_mfma_f32_16x16x32_bf16 v[156:159], v[156:159], v[108:111], 0
	s_waitcnt lgkmcnt(10)
	v_mfma_f32_16x16x32_bf16 v[144:147], v[160:163], v[68:71], v[144:147]
	v_mfma_f32_16x16x32_bf16 v[156:159], v[160:163], v[88:91], v[156:159]
	s_waitcnt lgkmcnt(9)
	v_mfma_f32_16x16x32_bf16 v[144:147], v[168:171], v[92:95], v[144:147]
	v_mfma_f32_16x16x32_bf16 v[156:159], v[168:171], v[112:115], v[156:159]
	s_waitcnt lgkmcnt(8)
	v_mfma_f32_16x16x32_bf16 v[144:147], v[172:175], v[80:83], v[144:147]
	v_mfma_f32_16x16x32_bf16 v[156:159], v[172:175], v[96:99], v[156:159]
	s_waitcnt lgkmcnt(7)
	v_mfma_f32_16x16x32_bf16 v[144:147], v[186:189], v[100:103], v[144:147]
	v_mfma_f32_16x16x32_bf16 v[160:163], v[186:189], v[116:119], v[156:159]
	s_waitcnt lgkmcnt(6)
	v_mfma_f32_16x16x32_bf16 v[156:159], v[206:209], v[84:87], v[144:147]
	v_mfma_f32_16x16x32_bf16 v[144:147], v[206:209], v[104:107], v[160:163]
	ds_read_b128 v[168:171], v182 offset:18432
	ds_read_b128 v[172:175], v182 offset:19456
	ds_read_b128 v[186:189], v182 offset:20480
	ds_read_b128 v[206:209], v182 offset:21504
	ds_read_b128 v[226:229], v182 offset:22528
	ds_read_b128 v[230:233], v182 offset:23552
	s_waitcnt lgkmcnt(11)
	v_mfma_f32_16x16x32_bf16 v[160:163], v[132:135], v[64:67], 0
	v_mfma_f32_16x16x32_bf16 v[132:135], v[132:135], v[108:111], 0
	s_waitcnt lgkmcnt(10)
	v_mfma_f32_16x16x32_bf16 v[160:163], v[140:143], v[68:71], v[160:163]
	v_mfma_f32_16x16x32_bf16 v[132:135], v[140:143], v[88:91], v[132:135]
	s_waitcnt lgkmcnt(9)
	v_mfma_f32_16x16x32_bf16 v[140:143], v[152:155], v[92:95], v[160:163]
	v_mfma_f32_16x16x32_bf16 v[132:135], v[152:155], v[112:115], v[132:135]
	s_waitcnt lgkmcnt(8)
	v_mfma_f32_16x16x32_bf16 v[140:143], v[210:213], v[80:83], v[140:143]
	v_mfma_f32_16x16x32_bf16 v[132:135], v[210:213], v[96:99], v[132:135]
	s_waitcnt lgkmcnt(7)
	v_mfma_f32_16x16x32_bf16 v[140:143], v[214:217], v[100:103], v[140:143]
	v_mfma_f32_16x16x32_bf16 v[132:135], v[214:217], v[116:119], v[132:135]
	s_waitcnt lgkmcnt(6)
	v_mfma_f32_16x16x32_bf16 v[160:163], v[218:221], v[84:87], v[140:143]
	v_mfma_f32_16x16x32_bf16 v[132:135], v[218:221], v[104:107], v[132:135]
	s_waitcnt lgkmcnt(5)
	v_mfma_f32_16x16x32_bf16 v[140:143], v[168:171], v[64:67], 0
	v_mfma_f32_16x16x32_bf16 v[152:155], v[168:171], v[108:111], 0
	s_waitcnt lgkmcnt(4)
	v_mfma_f32_16x16x32_bf16 v[140:143], v[172:175], v[68:71], v[140:143]
	v_mfma_f32_16x16x32_bf16 v[152:155], v[172:175], v[88:91], v[152:155]
	s_waitcnt lgkmcnt(3)
	v_mfma_f32_16x16x32_bf16 v[140:143], v[186:189], v[92:95], v[140:143]
	v_mfma_f32_16x16x32_bf16 v[152:155], v[186:189], v[112:115], v[152:155]
	s_waitcnt lgkmcnt(2)
	v_mfma_f32_16x16x32_bf16 v[140:143], v[206:209], v[80:83], v[140:143]
	v_mfma_f32_16x16x32_bf16 v[152:155], v[206:209], v[96:99], v[152:155]
	s_waitcnt lgkmcnt(1)
	v_mfma_f32_16x16x32_bf16 v[140:143], v[226:229], v[100:103], v[140:143]
	v_mfma_f32_16x16x32_bf16 v[168:171], v[226:229], v[116:119], v[152:155]
	s_waitcnt lgkmcnt(0)
	v_mfma_f32_16x16x32_bf16 v[152:155], v[230:233], v[84:87], v[140:143]
	v_mfma_f32_16x16x32_bf16 v[140:143], v[230:233], v[104:107], v[168:171]
	s_xor_b32 s98, s22, 1
	s_mul_i32 s98, s98, 0x6000
	v_add_u32_e32 v241, s98, v201
	s_waitcnt vmcnt(4)
	ds_write_b128 v241, v[72:75]
	s_waitcnt vmcnt(3)
	ds_write_b128 v241, v[76:79] offset:2048
	s_waitcnt vmcnt(2)
	ds_write_b128 v241, v[124:127] offset:4096
	s_waitcnt lgkmcnt(0)
	s_barrier
; #define LAS __attribute__((address_space(3)))
; template <int DQK, bool MB> ...
;     ...
;             for (int kk = 0; kk < KK; ++kk) kfa[kk] = *(const LAS bf16x8*)(kb + kk * 1024 + koff);
; #pragma unroll
;             for (int ks = 0; ks < 4; ++ks) {
;                 if (ks < 3) {
; #pragma unroll
;                     for (int kk = 0; kk < KK; ++kk) { const bf16x8 t = *(const LAS bf16x8*)(kb + ((ks + 1) * KK + kk) * 1024 + koff); if (ks & 1) kfa[kk] = t; else kfb[kk] = t; }
;                 }
;                 __builtin_amdgcn_sched_barrier(0);
;                 s[ks][0] = (f32x4){0.f, 0.f, 0.f, 0.f}; s[ks][1] = (f32x4){0.f, 0.f, 0.f, 0.f};
; #pragma unroll
;                 for (int kk = 0; kk < KK; ++kk) { const bf16x8 kf = (ks & 1) ? kfb[kk] : kfa[kk];
;                     const bf16x8 qa0 = qf[0][kk], qa1 = qf[1][kk];
;                     s[ks][0] = __builtin_amdgcn_mfma_f32_16x16x32_bf16(kf, qa0, s[ks][0], 0, 0, 0);
;                     s[ks][1] = __builtin_amdgcn_mfma_f32_16x16x32_bf16(kf, qa1, s[ks][1], 0, 0, 0); }
;                 __builtin_amdgcn_sched_barrier(0);
;             }
;     ...
;             } else if (64 * kt + 63 > wave_qmax - 31) {
; #pragma unroll
;                 for (int ks = 0; ks < 4; ++ks)
; #pragma unroll
;                     for (int j = 0; j < 4; ++j) { const int key = 64 * kt + 16 * ks + 4 * q + j;
;                         s[ks][0][j] = (key <= qi0) ? s[ks][0][j] : -INFINITY; s[ks][1][j] = (key <= qi1) ? s[ks][1][j] : -INFINITY; }
;             }
	s_add_i32 s0, s63, 63
	s_cmp_le_u32 s0, s61
	s_cbranch_scc1 .LBB0_496
	s_nop 1
	v_add_u32_e32 v168, s63, v199
	v_cmp_le_u32_e64 s[0:1], v168, v178
	v_add_u32_e32 v169, 2, v168
	v_cmp_gt_u32_e32 vcc, v168, v176
	v_cndmask_b32_e64 v136, v193, v136, s[0:1]
	v_cmp_lt_u32_e64 s[0:1], v168, v176
	v_cndmask_b32_e32 v148, v148, v193, vcc
	v_cndmask_b32_e32 v144, v144, v193, vcc
	v_cndmask_b32_e64 v149, v193, v149, s[0:1]
	v_cmp_lt_u32_e64 s[0:1], v168, v178
	s_nop 1
	v_cndmask_b32_e64 v137, v193, v137, s[0:1]
	v_cmp_le_u32_e64 s[0:1], v169, v176
	s_nop 1
	v_cndmask_b32_e64 v150, v193, v150, s[0:1]
	v_cmp_le_u32_e64 s[0:1], v169, v178
	v_add_u32_e32 v169, 3, v168
	s_nop 0
	v_cndmask_b32_e64 v138, v193, v138, s[0:1]
	v_cmp_le_u32_e64 s[0:1], v169, v176
	s_nop 1
	v_cndmask_b32_e64 v151, v193, v151, s[0:1]
	v_cmp_le_u32_e64 s[0:1], v169, v178
	v_add_u32_e32 v169, 16, v168
	s_nop 0
	v_cndmask_b32_e64 v139, v193, v139, s[0:1]
	v_cmp_le_u32_e64 s[0:1], v169, v176
	v_add_u32_e32 v169, 17, v168
	v_cmp_le_u32_e32 vcc, v169, v176
	v_cndmask_b32_e64 v156, v193, v156, s[0:1]
	s_nop 0
	v_cndmask_b32_e32 v157, v193, v157, vcc
	v_cmp_le_u32_e32 vcc, v169, v178
	v_add_u32_e32 v169, 18, v168
	s_nop 0
	v_cndmask_b32_e32 v145, v193, v145, vcc
	v_cmp_le_u32_e32 vcc, v169, v176
	s_nop 1
	v_cndmask_b32_e32 v158, v193, v158, vcc
	v_cmp_le_u32_e32 vcc, v169, v178
	v_add_u32_e32 v169, 19, v168
	s_nop 0
	v_cndmask_b32_e32 v146, v193, v146, vcc
	v_cmp_le_u32_e32 vcc, v169, v176
	s_nop 1
	v_cndmask_b32_e32 v159, v193, v159, vcc
	v_cmp_le_u32_e32 vcc, v169, v178
	v_add_u32_e32 v169, 32, v168
	s_nop 0
	v_cndmask_b32_e32 v147, v193, v147, vcc
	v_cmp_le_u32_e32 vcc, v169, v176
	s_nop 1
	v_cndmask_b32_e32 v160, v193, v160, vcc
	v_cmp_le_u32_e32 vcc, v169, v178
	v_add_u32_e32 v169, 33, v168
	s_nop 0
	v_cndmask_b32_e32 v132, v193, v132, vcc
	v_cmp_le_u32_e32 vcc, v169, v176
	s_nop 1
	v_cndmask_b32_e32 v161, v193, v161, vcc
	v_cmp_le_u32_e32 vcc, v169, v178
	v_add_u32_e32 v169, 34, v168
	s_nop 0
	v_cndmask_b32_e32 v133, v193, v133, vcc
	v_cmp_le_u32_e32 vcc, v169, v176
	s_nop 1
	v_cndmask_b32_e32 v162, v193, v162, vcc
	v_cmp_le_u32_e32 vcc, v169, v178
	v_add_u32_e32 v169, 35, v168
	s_nop 0
	v_cndmask_b32_e32 v134, v193, v134, vcc
	v_cmp_le_u32_e32 vcc, v169, v176
	s_nop 1
	v_cndmask_b32_e32 v163, v193, v163, vcc
	v_cmp_le_u32_e32 vcc, v169, v178
	v_add_u32_e32 v169, 48, v168
	s_nop 0
	v_cndmask_b32_e32 v135, v193, v135, vcc
	v_cmp_le_u32_e32 vcc, v169, v176
	s_nop 1
	v_cndmask_b32_e32 v152, v193, v152, vcc
	v_cmp_le_u32_e32 vcc, v169, v178
	v_add_u32_e32 v169, 49, v168
	s_nop 0
	v_cndmask_b32_e32 v140, v193, v140, vcc
	v_cmp_le_u32_e32 vcc, v169, v176
	s_nop 1
	v_cndmask_b32_e32 v153, v193, v153, vcc
	v_cmp_le_u32_e32 vcc, v169, v178
	v_add_u32_e32 v169, 50, v168
	v_add_u32_e32 v168, 51, v168
	v_cndmask_b32_e32 v141, v193, v141, vcc
	v_cmp_le_u32_e32 vcc, v169, v176
	s_nop 1
	v_cndmask_b32_e32 v154, v193, v154, vcc
	v_cmp_le_u32_e32 vcc, v169, v178
	s_nop 1
	v_cndmask_b32_e32 v142, v193, v142, vcc
	v_cmp_le_u32_e32 vcc, v168, v176
	s_nop 1
	v_cndmask_b32_e32 v155, v193, v155, vcc
	v_cmp_le_u32_e32 vcc, v168, v178
	s_nop 1
	v_cndmask_b32_e32 v143, v193, v143, vcc
	s_branch .LBB0_496
.LBB0_501:
	s_cmp_le_u32 s62, s64
	s_mov_b64 s[0:1], -1
	s_cbranch_scc0 .Lst_a_last_noact
	s_add_i32 s0, s65, 0
	v_add_u32_e32 v182, s0, v202
	ds_read_b128 v[72:75], v182
	ds_read_b128 v[76:79], v182 offset:1024
	ds_read_b128 v[120:123], v182 offset:2048
	ds_read_b128 v[124:127], v182 offset:3072
	ds_read_b128 v[128:131], v182 offset:4096
	ds_read_b128 v[132:135], v182 offset:5120
	ds_read_b128 v[136:139], v182 offset:6144
	ds_read_b128 v[140:143], v182 offset:7168
	ds_read_b128 v[144:147], v182 offset:8192
	ds_read_b128 v[148:151], v182 offset:9216
	ds_read_b128 v[152:155], v182 offset:10240
	ds_read_b128 v[156:159], v182 offset:11264
	s_waitcnt lgkmcnt(11)
	v_mfma_f32_16x16x32_bf16 v[160:163], v[72:75], v[64:67], 0
	v_mfma_f32_16x16x32_bf16 v[72:75], v[72:75], v[108:111], 0
	s_waitcnt lgkmcnt(10)
	v_mfma_f32_16x16x32_bf16 v[160:163], v[76:79], v[68:71], v[160:163]
	v_mfma_f32_16x16x32_bf16 v[72:75], v[76:79], v[88:91], v[72:75]
	s_waitcnt lgkmcnt(9)
	v_mfma_f32_16x16x32_bf16 v[76:79], v[120:123], v[92:95], v[160:163]
	v_mfma_f32_16x16x32_bf16 v[72:75], v[120:123], v[112:115], v[72:75]
	s_waitcnt lgkmcnt(8)
	v_mfma_f32_16x16x32_bf16 v[76:79], v[124:127], v[80:83], v[76:79]
	v_mfma_f32_16x16x32_bf16 v[72:75], v[124:127], v[96:99], v[72:75]
	s_waitcnt lgkmcnt(7)
	v_mfma_f32_16x16x32_bf16 v[76:79], v[128:131], v[100:103], v[76:79]
	v_mfma_f32_16x16x32_bf16 v[72:75], v[128:131], v[116:119], v[72:75]
	s_waitcnt lgkmcnt(6)
	v_mfma_f32_16x16x32_bf16 v[124:127], v[132:135], v[84:87], v[76:79]
	v_mfma_f32_16x16x32_bf16 v[76:79], v[132:135], v[104:107], v[72:75]
	ds_read_b128 v[120:123], v182 offset:12288
	ds_read_b128 v[132:135], v182 offset:13312
	ds_read_b128 v[160:163], v182 offset:14336
	ds_read_b128 v[164:167], v182 offset:15360
	ds_read_b128 v[168:171], v182 offset:16384
	ds_read_b128 v[172:175], v182 offset:17408
	s_waitcnt lgkmcnt(11)
	v_mfma_f32_16x16x32_bf16 v[72:75], v[136:139], v[64:67], 0
	v_mfma_f32_16x16x32_bf16 v[128:131], v[136:139], v[108:111], 0
	s_waitcnt lgkmcnt(10)
	v_mfma_f32_16x16x32_bf16 v[72:75], v[140:143], v[68:71], v[72:75]
	v_mfma_f32_16x16x32_bf16 v[128:131], v[140:143], v[88:91], v[128:131]
	s_waitcnt lgkmcnt(9)
	v_mfma_f32_16x16x32_bf16 v[72:75], v[144:147], v[92:95], v[72:75]
	v_mfma_f32_16x16x32_bf16 v[128:131], v[144:147], v[112:115], v[128:131]
	s_waitcnt lgkmcnt(8)
	v_mfma_f32_16x16x32_bf16 v[72:75], v[148:151], v[80:83], v[72:75]
	v_mfma_f32_16x16x32_bf16 v[128:131], v[148:151], v[96:99], v[128:131]
	s_waitcnt lgkmcnt(7)
; #define LAS __attribute__((address_space(3)))
; template <int DQK, bool MB> ...
;     ...
;             for (int ks = 0; ks < 4; ++ks) {
;                 if (ks < 3) {
; #pragma unroll
;                     for (int kk = 0; kk < KK; ++kk) { const bf16x8 t = *(const LAS bf16x8*)(kb + ((ks + 1) * KK + kk) * 1024 + koff); if (ks & 1) kfa[kk] = t; else kfb[kk] = t; }
;                 }
;                 __builtin_amdgcn_sched_barrier(0);
;                 s[ks][0] = (f32x4){0.f, 0.f, 0.f, 0.f}; s[ks][1] = (f32x4){0.f, 0.f, 0.f, 0.f};
; #pragma unroll
;                 for (int kk = 0; kk < KK; ++kk) { const bf16x8 kf = (ks & 1) ? kfb[kk] : kfa[kk];
;                     const bf16x8 qa0 = qf[0][kk], qa1 = qf[1][kk];
;                     s[ks][0] = __builtin_amdgcn_mfma_f32_16x16x32_bf16(kf, qa0, s[ks][0], 0, 0, 0);
;                     s[ks][1] = __builtin_amdgcn_mfma_f32_16x16x32_bf16(kf, qa1, s[ks][1], 0, 0, 0); }
;                 __builtin_amdgcn_sched_barrier(0);
;             }
;         }
;         if (ST) { asm volatile("" ::: "memory"); __builtin_amdgcn_s_barrier(); asm volatile("" ::: "memory"); }
;     ...
;             } else if (64 * kt + 63 > wave_qmax - 31) {
; #pragma unroll
;                 for (int ks = 0; ks < 4; ++ks)
; #pragma unroll
;                     for (int j = 0; j < 4; ++j) { const int key = 64 * kt + 16 * ks + 4 * q + j;
;                         s[ks][0][j] = (key <= qi0) ? s[ks][0][j] : -INFINITY; s[ks][1][j] = (key <= qi1) ? s[ks][1][j] : -INFINITY; }
;             }
	v_mfma_f32_16x16x32_bf16 v[72:75], v[152:155], v[100:103], v[72:75]
	v_mfma_f32_16x16x32_bf16 v[136:139], v[152:155], v[116:119], v[128:131]
	s_waitcnt lgkmcnt(6)
	v_mfma_f32_16x16x32_bf16 v[128:131], v[156:159], v[84:87], v[72:75]
	v_mfma_f32_16x16x32_bf16 v[72:75], v[156:159], v[104:107], v[136:139]
	s_nop 4
	ds_read_b128 v[136:139], v182 offset:18432
	ds_read_b128 v[140:143], v182 offset:19456
	ds_read_b128 v[144:147], v182 offset:20480
	ds_read_b128 v[148:151], v182 offset:21504
	ds_read_b128 v[152:155], v182 offset:22528
	ds_read_b128 v[156:159], v182 offset:23552
	s_waitcnt lgkmcnt(11)
	v_mfma_f32_16x16x32_bf16 v[186:189], v[120:123], v[64:67], 0
	v_mfma_f32_16x16x32_bf16 v[120:123], v[120:123], v[108:111], 0
	s_waitcnt lgkmcnt(10)
	v_mfma_f32_16x16x32_bf16 v[186:189], v[132:135], v[68:71], v[186:189]
	v_mfma_f32_16x16x32_bf16 v[120:123], v[132:135], v[88:91], v[120:123]
	s_waitcnt lgkmcnt(9)
	v_mfma_f32_16x16x32_bf16 v[132:135], v[160:163], v[92:95], v[186:189]
	v_mfma_f32_16x16x32_bf16 v[120:123], v[160:163], v[112:115], v[120:123]
	s_waitcnt lgkmcnt(8)
	v_mfma_f32_16x16x32_bf16 v[132:135], v[164:167], v[80:83], v[132:135]
	v_mfma_f32_16x16x32_bf16 v[120:123], v[164:167], v[96:99], v[120:123]
	s_waitcnt lgkmcnt(7)
	v_mfma_f32_16x16x32_bf16 v[132:135], v[168:171], v[100:103], v[132:135]
	v_mfma_f32_16x16x32_bf16 v[120:123], v[168:171], v[116:119], v[120:123]
	s_waitcnt lgkmcnt(6)
	v_mfma_f32_16x16x32_bf16 v[132:135], v[172:175], v[84:87], v[132:135]
	v_mfma_f32_16x16x32_bf16 v[120:123], v[172:175], v[104:107], v[120:123]
	s_waitcnt lgkmcnt(5)
	v_mfma_f32_16x16x32_bf16 v[64:67], v[136:139], v[64:67], 0
	v_mfma_f32_16x16x32_bf16 v[108:111], v[136:139], v[108:111], 0
	s_waitcnt lgkmcnt(4)
	v_mfma_f32_16x16x32_bf16 v[64:67], v[140:143], v[68:71], v[64:67]
	v_mfma_f32_16x16x32_bf16 v[68:71], v[140:143], v[88:91], v[108:111]
	s_waitcnt lgkmcnt(3)
	v_mfma_f32_16x16x32_bf16 v[64:67], v[144:147], v[92:95], v[64:67]
	v_mfma_f32_16x16x32_bf16 v[68:71], v[144:147], v[112:115], v[68:71]
	s_waitcnt lgkmcnt(2)
	v_mfma_f32_16x16x32_bf16 v[64:67], v[148:151], v[80:83], v[64:67]
	v_mfma_f32_16x16x32_bf16 v[68:71], v[148:151], v[96:99], v[68:71]
	s_waitcnt lgkmcnt(1)
	v_mfma_f32_16x16x32_bf16 v[64:67], v[152:155], v[100:103], v[64:67]
	v_mfma_f32_16x16x32_bf16 v[80:83], v[152:155], v[116:119], v[68:71]
	s_waitcnt lgkmcnt(0)
	v_mfma_f32_16x16x32_bf16 v[68:71], v[156:159], v[84:87], v[64:67]
	v_mfma_f32_16x16x32_bf16 v[64:67], v[156:159], v[104:107], v[80:83]
	s_barrier
	s_or_b32 s0, s62, 63
	s_cmp_le_u32 s0, s61
	s_cbranch_scc1 .LBB0_504
	s_nop 1
	v_or_b32_e32 v80, s62, v199
	v_cmp_le_u32_e64 s[0:1], v80, v178
	v_or_b32_e32 v81, 2, v80
	v_cmp_gt_u32_e32 vcc, v80, v176
	v_cndmask_b32_e64 v76, v193, v76, s[0:1]
	v_cmp_lt_u32_e64 s[0:1], v80, v176
	v_cndmask_b32_e32 v124, v124, v193, vcc
	v_cndmask_b32_e32 v72, v72, v193, vcc
	v_cndmask_b32_e64 v125, v193, v125, s[0:1]
	v_cmp_lt_u32_e64 s[0:1], v80, v178
	s_nop 1
	v_cndmask_b32_e64 v77, v193, v77, s[0:1]
	v_cmp_le_u32_e64 s[0:1], v81, v176
	s_nop 1
	v_cndmask_b32_e64 v126, v193, v126, s[0:1]
	v_cmp_le_u32_e64 s[0:1], v81, v178
	v_or_b32_e32 v81, 3, v80
	s_nop 0
	v_cndmask_b32_e64 v78, v193, v78, s[0:1]
	v_cmp_le_u32_e64 s[0:1], v81, v176
	s_nop 1
	v_cndmask_b32_e64 v127, v193, v127, s[0:1]
	v_cmp_le_u32_e64 s[0:1], v81, v178
	v_or_b32_e32 v81, 16, v80
	s_nop 0
	v_cndmask_b32_e64 v79, v193, v79, s[0:1]
	v_cmp_le_u32_e64 s[0:1], v81, v176
	v_or_b32_e32 v81, 17, v80
	v_cmp_le_u32_e32 vcc, v81, v176
	v_cndmask_b32_e64 v128, v193, v128, s[0:1]
	s_nop 0
	v_cndmask_b32_e32 v129, v193, v129, vcc
	v_cmp_le_u32_e32 vcc, v81, v178
	v_or_b32_e32 v81, 18, v80
	s_nop 0
	v_cndmask_b32_e32 v73, v193, v73, vcc
	v_cmp_le_u32_e32 vcc, v81, v176
	s_nop 1
	v_cndmask_b32_e32 v130, v193, v130, vcc
	v_cmp_le_u32_e32 vcc, v81, v178
	v_or_b32_e32 v81, 19, v80
	s_nop 0
	v_cndmask_b32_e32 v74, v193, v74, vcc
	v_cmp_le_u32_e32 vcc, v81, v176
	s_nop 1
	v_cndmask_b32_e32 v131, v193, v131, vcc
	v_cmp_le_u32_e32 vcc, v81, v178
	v_or_b32_e32 v81, 32, v80
	s_nop 0
	v_cndmask_b32_e32 v75, v193, v75, vcc
	v_cmp_le_u32_e32 vcc, v81, v176
	s_nop 1
	v_cndmask_b32_e32 v132, v193, v132, vcc
	v_cmp_le_u32_e32 vcc, v81, v178
	v_or_b32_e32 v81, 33, v80
	s_nop 0
	v_cndmask_b32_e32 v120, v193, v120, vcc
	v_cmp_le_u32_e32 vcc, v81, v176
	s_nop 1
	v_cndmask_b32_e32 v133, v193, v133, vcc
	v_cmp_le_u32_e32 vcc, v81, v178
	v_or_b32_e32 v81, 34, v80
	s_nop 0
	v_cndmask_b32_e32 v121, v193, v121, vcc
	v_cmp_le_u32_e32 vcc, v81, v176
	s_nop 1
	v_cndmask_b32_e32 v134, v193, v134, vcc
	v_cmp_le_u32_e32 vcc, v81, v178
	v_or_b32_e32 v81, 35, v80
	s_nop 0
	v_cndmask_b32_e32 v122, v193, v122, vcc
	v_cmp_le_u32_e32 vcc, v81, v176
	s_nop 1
	v_cndmask_b32_e32 v135, v193, v135, vcc
	v_cmp_le_u32_e32 vcc, v81, v178
	v_or_b32_e32 v81, 48, v80
	s_nop 0
	v_cndmask_b32_e32 v123, v193, v123, vcc
	v_cmp_le_u32_e32 vcc, v81, v176
	s_nop 1
	v_cndmask_b32_e32 v68, v193, v68, vcc
	v_cmp_le_u32_e32 vcc, v81, v178
	v_or_b32_e32 v81, 49, v80
	s_nop 0
	v_cndmask_b32_e32 v64, v193, v64, vcc
	v_cmp_le_u32_e32 vcc, v81, v176
	s_nop 1
	v_cndmask_b32_e32 v69, v193, v69, vcc
	v_cmp_le_u32_e32 vcc, v81, v178
	v_or_b32_e32 v81, 50, v80
	v_or_b32_e32 v80, 51, v80
	v_cndmask_b32_e32 v65, v193, v65, vcc
	v_cmp_le_u32_e32 vcc, v81, v176
	s_nop 1
	v_cndmask_b32_e32 v70, v193, v70, vcc
	v_cmp_le_u32_e32 vcc, v81, v178
	s_nop 1
	v_cndmask_b32_e32 v66, v193, v66, vcc
	v_cmp_le_u32_e32 vcc, v80, v176
	s_nop 1
	v_cndmask_b32_e32 v71, v193, v71, vcc
	v_cmp_le_u32_e32 vcc, v80, v178
	s_nop 1
	v_cndmask_b32_e32 v67, v193, v67, vcc

; #define LAS __attribute__((address_space(3)))
; template <int DQK, bool MB> ...
;     ...
;         const bool act = MB || 64 * kt <= wave_qmax;
;         const LAS unsigned char* kb = kbase + buf * KT_BYTES; const LAS unsigned char* vb = vbase + buf * VT_BYTES;
;         f32x4 s[4][2];
;         if (act) {
;     ...
;         if (ST) { asm volatile("" ::: "memory"); __builtin_amdgcn_s_barrier(); asm volatile("" ::: "memory"); }
.Lst_a_noact:
	s_xor_b32 s98, s22, 1
	s_mul_i32 s98, s98, 0x6000
	v_add_u32_e32 v241, s98, v201
	s_waitcnt vmcnt(4)
	ds_write_b128 v241, v[72:75]
	s_waitcnt vmcnt(3)
	ds_write_b128 v241, v[76:79] offset:2048
	s_waitcnt vmcnt(2)
	ds_write_b128 v241, v[124:127] offset:4096
	s_waitcnt lgkmcnt(0)
	s_barrier
	s_branch .LBB0_497
.Lst_a_last_noact:
	s_barrier
	s_branch .LBB0_505

; __global__ void __launch_bounds__(NTHREADS, 2) fwd_megakernel(Args a) {
	.amdhsa_kernel _Z14fwd_megakernel4Args
		.amdhsa_group_segment_fixed_size 0
		.amdhsa_private_segment_fixed_size 0
		.amdhsa_kernarg_size 408
		.amdhsa_user_sgpr_count 2
		.amdhsa_user_sgpr_dispatch_ptr 0
		.amdhsa_user_sgpr_queue_ptr 0
		.amdhsa_user_sgpr_kernarg_segment_ptr 1
		.amdhsa_user_sgpr_dispatch_id 0
		.amdhsa_user_sgpr_kernarg_preload_length 0
		.amdhsa_user_sgpr_kernarg_preload_offset 0
		.amdhsa_user_sgpr_private_segment_size 0
		.amdhsa_uses_dynamic_stack 0
		.amdhsa_enable_private_segment 0
		.amdhsa_system_sgpr_workgroup_id_x 1
		.amdhsa_system_sgpr_workgroup_id_y 0
		.amdhsa_system_sgpr_workgroup_id_z 0
		.amdhsa_system_sgpr_workgroup_info 0
		.amdhsa_system_vgpr_workitem_id 2
		.amdhsa_next_free_vgpr 242
		.amdhsa_next_free_sgpr 102
		.amdhsa_accum_offset 244
		.amdhsa_reserve_vcc 1
		.amdhsa_float_round_mode_32 0
		.amdhsa_float_round_mode_16_64 0
		.amdhsa_float_denorm_mode_32 3
		.amdhsa_float_denorm_mode_16_64 3
		.amdhsa_dx10_clamp 1
		.amdhsa_ieee_mode 1
		.amdhsa_fp16_overflow 0
		.amdhsa_tg_split 0
		.amdhsa_exception_fp_ieee_invalid_op 0
		.amdhsa_exception_fp_denorm_src 0
		.amdhsa_exception_fp_ieee_div_zero 0
		.amdhsa_exception_fp_ieee_overflow 0
		.amdhsa_exception_fp_ieee_underflow 0
		.amdhsa_exception_fp_ieee_inexact 0
		.amdhsa_exception_int_div_zero 0
	.end_amdhsa_kernel

; __global__ void __launch_bounds__(NTHREADS, 2) fwd_megakernel(Args a) {
amdhsa.kernels:
  - .agpr_count:     0
    .args:
      - .offset:         0
        .size:           152
        .value_kind:     by_value
      - .offset:         152
        .size:           4
        .value_kind:     hidden_block_count_x
      - .offset:         156
        .size:           4
        .value_kind:     hidden_block_count_y
      - .offset:         160
        .size:           4
        .value_kind:     hidden_block_count_z
      - .offset:         164
        .size:           2
        .value_kind:     hidden_group_size_x
      - .offset:         166
        .size:           2
        .value_kind:     hidden_group_size_y
      - .offset:         168
        .size:           2
        .value_kind:     hidden_group_size_z
      - .offset:         170
        .size:           2
        .value_kind:     hidden_remainder_x
      - .offset:         172
        .size:           2
        .value_kind:     hidden_remainder_y
      - .offset:         174
        .size:           2
        .value_kind:     hidden_remainder_z
      - .offset:         192
        .size:           8
        .value_kind:     hidden_global_offset_x
      - .offset:         200
        .size:           8
        .value_kind:     hidden_global_offset_y
      - .offset:         208
        .size:           8
        .value_kind:     hidden_global_offset_z
      - .offset:         216
        .size:           2
        .value_kind:     hidden_grid_dims
      - .offset:         240
        .size:           8
        .value_kind:     hidden_multigrid_sync_arg
      - .offset:         272
        .size:           4
        .value_kind:     hidden_dynamic_lds_size
    .group_segment_fixed_size: 0
    .kernarg_segment_align: 8
    .kernarg_segment_size: 408
    .language:       OpenCL C
    .language_version:
      - 2
      - 0
    .max_flat_workgroup_size: 512
    .name:           _Z14fwd_megakernel4Args
    .private_segment_fixed_size: 0
    .sgpr_count:     108
    .sgpr_spill_count: 3
    .symbol:         _Z14fwd_megakernel4Args.kd
    .uniform_work_group_size: 1
    .uses_dynamic_stack: false
    .vgpr_count:     242
    .vgpr_spill_count: 0
    .wavefront_size: 64
